# k10 + one static s_setprio 1 for waves 4-7 over each differential block (reset to 0 at the block exit barrier)
# speedup vs baseline: 1.0024x; 1.0024x over previous
.LBB0_396:
	s_cmp_ge_u32 s3, 4
	s_cbranch_scc0 .Lprio_skip
	s_setprio 1

.LBB0_407:
	s_setprio 0
	s_barrier
	s_and_saveexec_b64 s[54:55], s[4:5]
	s_cbranch_execz .LBB0_395
	ds_write_b32 v205, v214
	s_branch .LBB0_395
